# prologue weight conversion: the eight RMSNorm gain scalars of a tile fetched in one round trip instead of eight drained ones
# baseline (speedup 1.0000x reference)
.LBB0_93:
	s_lshr_b32 s72, s62, 8
	v_cvt_f32_u32_e32 v64, s72
	s_sub_i32 s22, 0, s72
	s_ashr_i32 s73, s59, 2
	s_abs_i32 s5, s73
	v_rcp_iflag_f32_e32 v64, v64
	s_ashr_i32 s4, s59, 31
	s_waitcnt vmcnt(7)
	v_mov_b32_e32 v66, v0
	v_mov_b32_e32 v67, v1
	v_mul_f32_e32 v64, 0x4f7ffffe, v64
	v_cvt_u32_f32_e32 v64, v64
	v_mov_b32_e32 v65, v3
	v_readfirstlane_b32 s23, v64
	s_mul_i32 s22, s22, s23
	s_mul_hi_u32 s22, s23, s22
	s_add_i32 s23, s23, s22
	s_mul_hi_u32 s22, s5, s23
	s_mul_i32 s23, s22, s72
	s_sub_i32 s5, s5, s23
	s_add_i32 s24, s22, 1
	s_sub_i32 s23, s5, s72
	s_cmp_ge_u32 s5, s72
	s_cselect_b32 s22, s24, s22
	s_cselect_b32 s5, s23, s5
	s_add_i32 s23, s22, 1
	s_cmp_ge_u32 s5, s72
	s_cselect_b32 s5, s23, s22
	s_xor_b32 s5, s5, s4
	s_lshl_b32 s22, s59, 6
	s_sub_i32 s74, s5, s4
	s_and_b32 s22, s22, 0xc0
	s_lshl_b32 s4, s74, 8
	s_or_b32 s28, s4, s22
	s_cmp_lg_u64 s[0:1], 0
	s_cselect_b64 s[22:23], -1, 0
	s_cmp_eq_u64 s[0:1], 0
	v_mov_b32_e32 v64, v2
	s_cbranch_scc1 .LBB0_95
	v_add_u32_e32 v64, s28, v68
	v_ashrrev_i32_e32 v65, 31, v64
	v_lshl_add_u64 v[64:65], v[64:65], 2, s[0:1]
	global_load_dword v121, v[64:65], off offset:32
	global_load_dword v122, v[64:65], off offset:64
	global_load_dword v123, v[64:65], off offset:96
	global_load_dword v124, v[64:65], off offset:128
	global_load_dword v125, v[64:65], off offset:160
	global_load_dword v126, v[64:65], off offset:192
	global_load_dword v127, v[64:65], off offset:224
	global_load_dword v66, v[64:65], off
	s_waitcnt vmcnt(0)
	v_pk_mul_f32 v[64:65], v[2:3], v[66:67] op_sel_hi:[1,0]
	v_pk_mul_f32 v[66:67], v[0:1], v[66:67] op_sel_hi:[1,0]
.LBB0_95:
	s_nop 0
	v_cvt_pk_bf16_f32 v66, v66, v67
	v_cvt_pk_bf16_f32 v64, v64, v65
	v_add_u32_e32 v82, v71, v76
	ds_write2_b32 v82, v66, v64 offset1:1
	v_cndmask_b32_e64 v64, 0, 1, s[22:23]
	v_cmp_ne_u32_e64 s[4:5], 1, v64
	s_andn2_b64 vcc, exec, s[22:23]
	s_waitcnt vmcnt(6)
	v_mov_b32_e32 v66, v4
	v_mov_b32_e32 v67, v5
	v_mov_b32_e32 v64, v6
	v_mov_b32_e32 v65, v7
	s_cbranch_vccnz .LBB0_97
	s_ashr_i32 s29, s28, 31
	v_lshl_add_u64 v[64:65], s[28:29], 0, v[68:69]
	v_lshl_add_u64 v[64:65], v[64:65], 2, s[0:1]
	v_mov_b32_e32 v66, v121
	v_pk_mul_f32 v[64:65], v[6:7], v[66:67] op_sel_hi:[1,0]
	v_pk_mul_f32 v[66:67], v[4:5], v[66:67] op_sel_hi:[1,0]
.LBB0_97:
	s_movk_i32 s22, 0x1020
	v_cvt_pk_bf16_f32 v66, v66, v67
	v_cvt_pk_bf16_f32 v64, v64, v65
	v_add3_u32 v83, v71, v76, s22
	ds_write2_b32 v83, v66, v64 offset1:1
	s_and_b64 vcc, exec, s[4:5]
	s_waitcnt vmcnt(5)
	v_mov_b32_e32 v66, v8
	v_mov_b32_e32 v67, v9
	v_mov_b32_e32 v64, v10
	v_mov_b32_e32 v65, v11
	s_cbranch_vccnz .LBB0_99
	s_ashr_i32 s29, s28, 31
	v_lshl_add_u64 v[64:65], s[28:29], 0, v[68:69]
	v_lshl_add_u64 v[64:65], v[64:65], 2, s[0:1]
	v_mov_b32_e32 v66, v122
	v_pk_mul_f32 v[64:65], v[10:11], v[66:67] op_sel_hi:[1,0]
	v_pk_mul_f32 v[66:67], v[8:9], v[66:67] op_sel_hi:[1,0]
.LBB0_99:
	s_movk_i32 s22, 0x2040
	v_cvt_pk_bf16_f32 v66, v66, v67
	v_cvt_pk_bf16_f32 v64, v64, v65
	v_add3_u32 v84, v71, v76, s22
	ds_write2_b32 v84, v66, v64 offset1:1
	s_and_b64 vcc, exec, s[4:5]
	s_waitcnt vmcnt(4)
	v_mov_b32_e32 v66, v12
	v_mov_b32_e32 v67, v13
	v_mov_b32_e32 v64, v14
	v_mov_b32_e32 v65, v15
	s_cbranch_vccnz .LBB0_101
	s_ashr_i32 s29, s28, 31
	v_lshl_add_u64 v[64:65], s[28:29], 0, v[68:69]
	v_lshl_add_u64 v[64:65], v[64:65], 2, s[0:1]
	v_mov_b32_e32 v66, v123
	v_pk_mul_f32 v[64:65], v[14:15], v[66:67] op_sel_hi:[1,0]
	v_pk_mul_f32 v[66:67], v[12:13], v[66:67] op_sel_hi:[1,0]
.LBB0_101:
	s_movk_i32 s22, 0x3060
	v_cvt_pk_bf16_f32 v66, v66, v67
	v_cvt_pk_bf16_f32 v64, v64, v65
	v_add3_u32 v85, v71, v76, s22
	ds_write2_b32 v85, v66, v64 offset1:1
	s_and_b64 vcc, exec, s[4:5]
	s_waitcnt vmcnt(3)
	v_mov_b32_e32 v66, v16
	v_mov_b32_e32 v67, v17
	v_mov_b32_e32 v64, v18
	v_mov_b32_e32 v65, v19
	s_cbranch_vccnz .LBB0_103
	s_ashr_i32 s29, s28, 31
	v_lshl_add_u64 v[64:65], s[28:29], 0, v[68:69]
	v_lshl_add_u64 v[64:65], v[64:65], 2, s[0:1]
	v_mov_b32_e32 v66, v124
	v_pk_mul_f32 v[64:65], v[18:19], v[66:67] op_sel_hi:[1,0]
	v_pk_mul_f32 v[66:67], v[16:17], v[66:67] op_sel_hi:[1,0]
.LBB0_103:
	s_movk_i32 s22, 0x4080
	v_cvt_pk_bf16_f32 v66, v66, v67
	v_cvt_pk_bf16_f32 v64, v64, v65
	v_add3_u32 v86, v71, v76, s22
	ds_write2_b32 v86, v66, v64 offset1:1
	s_and_b64 vcc, exec, s[4:5]
	s_waitcnt vmcnt(2)
	v_mov_b32_e32 v66, v20
	v_mov_b32_e32 v67, v21
	v_mov_b32_e32 v64, v22
	v_mov_b32_e32 v65, v23
	s_cbranch_vccnz .LBB0_105
	s_ashr_i32 s29, s28, 31
	v_lshl_add_u64 v[64:65], s[28:29], 0, v[68:69]
	v_lshl_add_u64 v[64:65], v[64:65], 2, s[0:1]
	v_mov_b32_e32 v66, v125
	v_pk_mul_f32 v[64:65], v[22:23], v[66:67] op_sel_hi:[1,0]
	v_pk_mul_f32 v[66:67], v[20:21], v[66:67] op_sel_hi:[1,0]
.LBB0_105:
	s_movk_i32 s22, 0x50a0
	v_cvt_pk_bf16_f32 v66, v66, v67
	v_cvt_pk_bf16_f32 v64, v64, v65
	v_add3_u32 v87, v71, v76, s22
	ds_write2_b32 v87, v66, v64 offset1:1
	s_and_b64 vcc, exec, s[4:5]
	s_waitcnt vmcnt(1)
	v_mov_b32_e32 v66, v24
	v_mov_b32_e32 v67, v25
	v_mov_b32_e32 v64, v26
	v_mov_b32_e32 v65, v27
	s_cbranch_vccnz .LBB0_107
	s_ashr_i32 s29, s28, 31
	v_lshl_add_u64 v[64:65], s[28:29], 0, v[68:69]
	v_lshl_add_u64 v[64:65], v[64:65], 2, s[0:1]
	v_mov_b32_e32 v66, v126
	v_pk_mul_f32 v[64:65], v[26:27], v[66:67] op_sel_hi:[1,0]
	v_pk_mul_f32 v[66:67], v[24:25], v[66:67] op_sel_hi:[1,0]
.LBB0_107:
	s_movk_i32 s22, 0x60c0
	v_cvt_pk_bf16_f32 v66, v66, v67
	v_cvt_pk_bf16_f32 v64, v64, v65
	v_add3_u32 v88, v71, v76, s22
	ds_write2_b32 v88, v66, v64 offset1:1
	s_and_b64 vcc, exec, s[4:5]
	s_waitcnt vmcnt(0)
	v_mov_b32_e32 v66, v28
	v_mov_b32_e32 v67, v29
	v_mov_b32_e32 v64, v30
	v_mov_b32_e32 v65, v31
	s_cbranch_vccnz .LBB0_109
	s_ashr_i32 s29, s28, 31
	v_lshl_add_u64 v[64:65], s[28:29], 0, v[68:69]
	v_lshl_add_u64 v[64:65], v[64:65], 2, s[0:1]
	v_mov_b32_e32 v66, v127
	v_pk_mul_f32 v[64:65], v[30:31], v[66:67] op_sel_hi:[1,0]
	v_pk_mul_f32 v[66:67], v[28:29], v[66:67] op_sel_hi:[1,0]

.LBB0_180:
	s_mul_i32 s74, s74, s72
	s_sub_i32 s4, s73, s74
	s_ashr_i32 s29, s28, 31
	s_lshl_b32 s30, s4, 8
	s_lshl_b64 s[4:5], s[28:29], 1
	s_add_u32 s2, s2, s4
	s_addc_u32 s3, s3, s5
	v_mov_b32_e32 v75, v73
	v_lshl_add_u64 v[90:91], s[2:3], 0, v[74:75]
	ds_read_u16 v64, v81 offset:3096
	ds_read_u16 v65, v81 offset:3612
	ds_read_u16 v75, v81 offset:3224
	ds_read_u16 v96, v81 offset:3740
	ds_read_u16 v97, v81 offset:3352
	ds_read_u16 v98, v81 offset:3868
	ds_read_u16 v99, v81 offset:3996
	ds_read_u16 v100, v81 offset:3480
	s_waitcnt lgkmcnt(6)
	v_perm_b32 v67, v65, v64, s65
	ds_read_u16 v64, v81 offset:2064
	ds_read_u16 v65, v81 offset:2580
	ds_read_u16 v101, v81 offset:2192
	ds_read_u16 v102, v81 offset:2708
	ds_read_u16 v103, v81 offset:2320
	ds_read_u16 v104, v81 offset:2836
	ds_read_u16 v105, v81 offset:2964
	ds_read_u16 v106, v81 offset:2448
	s_waitcnt lgkmcnt(6)
	v_perm_b32 v66, v65, v64, s65
	ds_read_u16 v64, v81 offset:1032
	ds_read_u16 v65, v81 offset:1548
	ds_read_u16 v107, v81 offset:1160
	ds_read_u16 v108, v81 offset:1676
	ds_read_u16 v109, v81 offset:1288
	ds_read_u16 v110, v81 offset:1804
	ds_read_u16 v111, v81 offset:1932
	ds_read_u16 v112, v81 offset:1416
	s_waitcnt lgkmcnt(6)
	v_perm_b32 v65, v65, v64, s65
	ds_read_u16 v64, v81
	ds_read_u16 v72, v81 offset:516
	ds_read_u16 v113, v81 offset:128
	ds_read_u16 v114, v81 offset:644
	ds_read_u16 v115, v81 offset:256
	ds_read_u16 v116, v81 offset:772
	ds_read_u16 v117, v81 offset:900
	ds_read_u16 v118, v81 offset:384
	s_waitcnt lgkmcnt(6)
	v_perm_b32 v64, v72, v64, s65
	v_add_u32_e32 v72, s30, v77
	v_mad_u64_u32 v[92:93], s[2:3], v72, s67, 0
	v_ashrrev_i32_e32 v94, 31, v72
	v_mov_b32_e32 v72, v93
	v_mad_u64_u32 v[94:95], s[2:3], v94, s67, v[72:73]
	v_mov_b32_e32 v93, v94
	v_lshl_add_u64 v[92:93], v[92:93], 1, v[90:91]
	v_add_u32_e32 v72, s30, v78
	global_store_dwordx4 v[92:93], v[64:67], off
	v_mad_u64_u32 v[92:93], s[2:3], v72, s67, 0
	s_nop 0
	v_perm_b32 v67, v96, v75, s65
	v_ashrrev_i32_e32 v75, 31, v72
	v_mov_b32_e32 v72, v93
	v_mad_u64_u32 v[94:95], s[2:3], v75, s67, v[72:73]
	v_mov_b32_e32 v93, v94
	v_perm_b32 v66, v102, v101, s65
	v_perm_b32 v65, v108, v107, s65
	s_waitcnt lgkmcnt(4)
	v_perm_b32 v64, v114, v113, s65
	v_lshl_add_u64 v[92:93], v[92:93], 1, v[90:91]
	v_add_u32_e32 v72, s30, v79
	global_store_dwordx4 v[92:93], v[64:67], off
	v_mad_u64_u32 v[92:93], s[2:3], v72, s67, 0
	v_ashrrev_i32_e32 v75, 31, v72
	v_mov_b32_e32 v72, v93
	v_mad_u64_u32 v[94:95], s[2:3], v75, s67, v[72:73]
	v_mov_b32_e32 v93, v94
	v_perm_b32 v67, v98, v97, s65
	v_perm_b32 v66, v104, v103, s65
	v_perm_b32 v65, v110, v109, s65
	s_waitcnt lgkmcnt(2)
	v_perm_b32 v64, v116, v115, s65
	v_lshl_add_u64 v[92:93], v[92:93], 1, v[90:91]
	v_add_u32_e32 v72, s30, v80
	global_store_dwordx4 v[92:93], v[64:67], off
	v_mad_u64_u32 v[92:93], s[2:3], v72, s67, 0
	v_ashrrev_i32_e32 v75, 31, v72
	v_mov_b32_e32 v72, v93
	v_mad_u64_u32 v[94:95], s[2:3], v75, s67, v[72:73]
	s_or_b32 s2, s71, s66
	v_mov_b32_e32 v93, v94
	s_or_b32 s2, s2, 1
	v_perm_b32 v67, v99, v100, s65
	v_perm_b32 v66, v105, v106, s65
	v_perm_b32 v65, v111, v112, s65
	s_waitcnt lgkmcnt(0)
	v_perm_b32 v64, v117, v118, s65
	v_lshl_add_u64 v[90:91], v[92:93], 1, v[90:91]
	s_cmpk_gt_i32 s2, 0x223f
	global_store_dwordx4 v[90:91], v[64:67], off
	s_barrier
	s_cbranch_scc1 .LBB0_92
	s_lshr_b32 s66, s61, 8
	v_cvt_f32_u32_e32 v64, s66
	s_sub_i32 s4, 0, s66
	s_ashr_i32 s67, s63, 2
	s_abs_i32 s3, s67
	v_rcp_iflag_f32_e32 v64, v64
	s_ashr_i32 s2, s63, 31
	v_mul_f32_e32 v64, 0x4f7ffffe, v64
	v_cvt_u32_f32_e32 v64, v64
	s_nop 0
	v_readfirstlane_b32 s5, v64
	s_mul_i32 s4, s4, s5
	s_mul_hi_u32 s4, s5, s4
	s_add_i32 s5, s5, s4
	s_mul_hi_u32 s4, s3, s5
	s_mul_i32 s5, s4, s66
	s_sub_i32 s3, s3, s5
	s_add_i32 s28, s4, 1
	s_sub_i32 s5, s3, s66
	s_cmp_ge_u32 s3, s66
	s_cselect_b32 s4, s28, s4
	s_cselect_b32 s3, s5, s3
	s_add_i32 s5, s4, 1
	s_cmp_ge_u32 s3, s66
	s_cselect_b32 s3, s5, s4
	s_xor_b32 s3, s3, s2
	s_lshl_b32 s4, s63, 6
	s_sub_i32 s71, s3, s2
	s_and_b32 s4, s4, 0xc0
	s_lshl_b32 s2, s71, 8
	s_or_b32 s2, s2, s4
	s_cmp_lg_u64 s[80:81], 0
	v_mov_b64_e32 v[66:67], v[34:35]
	s_cselect_b64 s[28:29], -1, 0
	s_cmp_eq_u64 s[80:81], 0
	v_mov_b64_e32 v[64:65], v[32:33]
	s_cbranch_scc1 .LBB0_183
	v_add_u32_e32 v64, s2, v68
	v_ashrrev_i32_e32 v65, 31, v64
	v_lshl_add_u64 v[64:65], v[64:65], 2, s[80:81]
	global_load_dword v129, v[64:65], off offset:32
	global_load_dword v130, v[64:65], off offset:64
	global_load_dword v131, v[64:65], off offset:96
	global_load_dword v132, v[64:65], off offset:128
	global_load_dword v133, v[64:65], off offset:160
	global_load_dword v134, v[64:65], off offset:192
	global_load_dword v135, v[64:65], off offset:224
	global_load_dword v64, v[64:65], off
	s_waitcnt vmcnt(0)
	v_pk_mul_f32 v[66:67], v[34:35], v[64:65] op_sel_hi:[1,0]
	v_pk_mul_f32 v[64:65], v[32:33], v[64:65] op_sel_hi:[1,0]
.LBB0_183:
	s_nop 0
	v_cvt_pk_bf16_f32 v64, v64, v65
	v_cvt_pk_bf16_f32 v65, v66, v67
	ds_write2_b32 v82, v64, v65 offset1:1
	v_cndmask_b32_e64 v64, 0, 1, s[28:29]
	v_cmp_ne_u32_e64 s[4:5], 1, v64
	v_mov_b64_e32 v[66:67], v[38:39]
	s_andn2_b64 vcc, exec, s[28:29]
	v_mov_b64_e32 v[64:65], v[36:37]
	s_cbranch_vccnz .LBB0_185
	s_ashr_i32 s3, s2, 31
	v_lshl_add_u64 v[64:65], s[2:3], 0, v[68:69]
	v_lshl_add_u64 v[64:65], v[64:65], 2, s[80:81]
	v_mov_b32_e32 v64, v129
	v_pk_mul_f32 v[66:67], v[38:39], v[64:65] op_sel_hi:[1,0]
	v_pk_mul_f32 v[64:65], v[36:37], v[64:65] op_sel_hi:[1,0]
.LBB0_185:
	s_nop 0
	v_cvt_pk_bf16_f32 v64, v64, v65
	v_cvt_pk_bf16_f32 v65, v66, v67
	ds_write2_b32 v83, v64, v65 offset1:1
	v_mov_b64_e32 v[66:67], v[42:43]
	s_and_b64 vcc, exec, s[4:5]
	v_mov_b64_e32 v[64:65], v[40:41]
	s_cbranch_vccnz .LBB0_187
	s_ashr_i32 s3, s2, 31
	v_lshl_add_u64 v[64:65], s[2:3], 0, v[68:69]
	v_lshl_add_u64 v[64:65], v[64:65], 2, s[80:81]
	v_mov_b32_e32 v64, v130
	v_pk_mul_f32 v[66:67], v[42:43], v[64:65] op_sel_hi:[1,0]
	v_pk_mul_f32 v[64:65], v[40:41], v[64:65] op_sel_hi:[1,0]
.LBB0_187:
	s_nop 0
	v_cvt_pk_bf16_f32 v64, v64, v65
	v_cvt_pk_bf16_f32 v65, v66, v67
	ds_write2_b32 v84, v64, v65 offset1:1
	v_mov_b64_e32 v[66:67], v[46:47]
	s_and_b64 vcc, exec, s[4:5]
	v_mov_b64_e32 v[64:65], v[44:45]
	s_cbranch_vccnz .LBB0_189
	s_ashr_i32 s3, s2, 31
	v_lshl_add_u64 v[64:65], s[2:3], 0, v[68:69]
	v_lshl_add_u64 v[64:65], v[64:65], 2, s[80:81]
	v_mov_b32_e32 v64, v131
	v_pk_mul_f32 v[66:67], v[46:47], v[64:65] op_sel_hi:[1,0]
	v_pk_mul_f32 v[64:65], v[44:45], v[64:65] op_sel_hi:[1,0]
.LBB0_189:
	s_nop 0
	v_cvt_pk_bf16_f32 v64, v64, v65
	v_cvt_pk_bf16_f32 v65, v66, v67
	ds_write2_b32 v85, v64, v65 offset1:1
	v_mov_b64_e32 v[66:67], v[50:51]
	s_and_b64 vcc, exec, s[4:5]
	v_mov_b64_e32 v[64:65], v[48:49]
	s_cbranch_vccnz .LBB0_191
	s_ashr_i32 s3, s2, 31
	v_lshl_add_u64 v[64:65], s[2:3], 0, v[68:69]
	v_lshl_add_u64 v[64:65], v[64:65], 2, s[80:81]
	v_mov_b32_e32 v64, v132
	v_pk_mul_f32 v[66:67], v[50:51], v[64:65] op_sel_hi:[1,0]
	v_pk_mul_f32 v[64:65], v[48:49], v[64:65] op_sel_hi:[1,0]
.LBB0_191:
	s_nop 0
	v_cvt_pk_bf16_f32 v64, v64, v65
	v_cvt_pk_bf16_f32 v65, v66, v67
	ds_write2_b32 v86, v64, v65 offset1:1
	v_mov_b64_e32 v[66:67], v[54:55]
	s_and_b64 vcc, exec, s[4:5]
	v_mov_b64_e32 v[64:65], v[52:53]
	s_cbranch_vccnz .LBB0_193
	s_ashr_i32 s3, s2, 31
	v_lshl_add_u64 v[64:65], s[2:3], 0, v[68:69]
	v_lshl_add_u64 v[64:65], v[64:65], 2, s[80:81]
	v_mov_b32_e32 v64, v133
	v_pk_mul_f32 v[66:67], v[54:55], v[64:65] op_sel_hi:[1,0]
	v_pk_mul_f32 v[64:65], v[52:53], v[64:65] op_sel_hi:[1,0]
.LBB0_193:
	s_nop 0
	v_cvt_pk_bf16_f32 v64, v64, v65
	v_cvt_pk_bf16_f32 v65, v66, v67
	ds_write2_b32 v87, v64, v65 offset1:1
	v_mov_b64_e32 v[66:67], v[58:59]
	s_and_b64 vcc, exec, s[4:5]
	v_mov_b64_e32 v[64:65], v[56:57]
	s_cbranch_vccnz .LBB0_195
	s_ashr_i32 s3, s2, 31
	v_lshl_add_u64 v[64:65], s[2:3], 0, v[68:69]
	v_lshl_add_u64 v[64:65], v[64:65], 2, s[80:81]
	v_mov_b32_e32 v64, v134
	v_pk_mul_f32 v[66:67], v[58:59], v[64:65] op_sel_hi:[1,0]
	v_pk_mul_f32 v[64:65], v[56:57], v[64:65] op_sel_hi:[1,0]
.LBB0_195:
	s_nop 0
	v_cvt_pk_bf16_f32 v64, v64, v65
	v_cvt_pk_bf16_f32 v65, v66, v67
	ds_write2_b32 v88, v64, v65 offset1:1
	v_mov_b64_e32 v[66:67], v[62:63]
	s_and_b64 vcc, exec, s[4:5]
	v_mov_b64_e32 v[64:65], v[60:61]
	s_cbranch_vccnz .LBB0_197
	s_ashr_i32 s3, s2, 31
	v_lshl_add_u64 v[64:65], s[2:3], 0, v[68:69]
	v_lshl_add_u64 v[64:65], v[64:65], 2, s[80:81]
	v_mov_b32_e32 v64, v135
	v_pk_mul_f32 v[66:67], v[62:63], v[64:65] op_sel_hi:[1,0]
	v_pk_mul_f32 v[64:65], v[60:61], v[64:65] op_sel_hi:[1,0]
